# v79 + first arriver of each XCC issues an early L2 writeback hint at the grid barrier
# baseline (speedup 1.0000x reference)
.LBB0_82:
	s_or_b64 exec, exec, s[12:13]
	v_cvt_f32_u32_e32 v4, v2
	s_waitcnt vmcnt(0)
	v_readfirstlane_b32 s0, v3
	v_sub_u32_e32 v3, 0, v2
	v_rcp_iflag_f32_e32 v4, v4
	v_add_u32_e32 v5, s0, v1
	v_mul_f32_e32 v4, 0x4f7ffffe, v4
	v_cvt_u32_f32_e32 v4, v4
	v_mul_lo_u32 v1, v3, v4
	v_mul_hi_u32 v1, v4, v1
	v_add_u32_e32 v1, v4, v1
	v_mul_hi_u32 v1, v5, v1
	v_mul_lo_u32 v3, v1, v2
	v_sub_u32_e32 v3, v5, v3
	v_add_u32_e32 v4, 1, v1
	v_cmp_ge_u32_e32 vcc, v3, v2
	s_nop 1
	v_cndmask_b32_e32 v1, v1, v4, vcc
	v_sub_u32_e32 v4, v3, v2
	v_cndmask_b32_e32 v3, v3, v4, vcc
	v_add_u32_e32 v4, 1, v1
	v_cmp_ge_u32_e32 vcc, v3, v2
	v_add_u32_e32 v3, 1, v5
	s_nop 0
	v_cndmask_b32_e32 v1, v1, v4, vcc
	v_mul_lo_u32 v4, v2, v1
	v_add_u32_e32 v2, v4, v2
	v_cmp_ne_u32_e32 vcc, v3, v2
	s_and_saveexec_b64 s[0:1], vcc
	s_xor_b64 s[10:11], exec, s[0:1]
	s_cbranch_execz .LBB0_96
	s_waitcnt lgkmcnt(0)
	v_cmp_eq_u32_e32 vcc, v5, v4
	s_cbranch_vccz .Lxbw_0
	buffer_wbl2 sc1
.Lxbw_0:
	s_add_u32 s16, s6, 0x32d3500
	s_addc_u32 s17, s7, 0
	v_mov_b32_e32 v0, 0
	global_load_dword v0, v0, s[16:17] sc1
	s_waitcnt vmcnt(0)
	v_cmp_eq_u32_e32 vcc, v0, v1
	s_and_saveexec_b64 s[12:13], vcc
	s_cbranch_execz .LBB0_95
	s_add_u32 s14, s6, 0x32d0200
	s_addc_u32 s15, s7, 0
	s_mov_b32 s0, 1
	s_mov_b64 s[18:19], 0
	v_mov_b32_e32 v0, 0
	s_branch .LBB0_86

.LBB0_218:
	s_or_b64 exec, exec, s[12:13]
	v_cvt_f32_u32_e32 v4, v2
	s_waitcnt vmcnt(0)
	v_readfirstlane_b32 s0, v3
	v_sub_u32_e32 v3, 0, v2
	v_rcp_iflag_f32_e32 v4, v4
	v_add_u32_e32 v5, s0, v1
	v_mul_f32_e32 v4, 0x4f7ffffe, v4
	v_cvt_u32_f32_e32 v4, v4
	v_mul_lo_u32 v1, v3, v4
	v_mul_hi_u32 v1, v4, v1
	v_add_u32_e32 v1, v4, v1
	v_mul_hi_u32 v1, v5, v1
	v_mul_lo_u32 v3, v1, v2
	v_sub_u32_e32 v3, v5, v3
	v_add_u32_e32 v4, 1, v1
	v_cmp_ge_u32_e32 vcc, v3, v2
	s_nop 1
	v_cndmask_b32_e32 v1, v1, v4, vcc
	v_sub_u32_e32 v4, v3, v2
	v_cndmask_b32_e32 v3, v3, v4, vcc
	v_add_u32_e32 v4, 1, v1
	v_cmp_ge_u32_e32 vcc, v3, v2
	v_add_u32_e32 v3, 1, v5
	s_nop 0
	v_cndmask_b32_e32 v1, v1, v4, vcc
	v_mul_lo_u32 v4, v2, v1
	v_add_u32_e32 v2, v4, v2
	v_cmp_ne_u32_e32 vcc, v3, v2
	s_and_saveexec_b64 s[0:1], vcc
	s_xor_b64 s[8:9], exec, s[0:1]
	s_cbranch_execz .LBB0_232
	s_waitcnt lgkmcnt(0)
	v_cmp_eq_u32_e32 vcc, v5, v4
	s_cbranch_vccz .Lxbw_1
	buffer_wbl2 sc1
.Lxbw_1:
	s_add_u32 s16, s10, 0x32d3500
	s_addc_u32 s17, s11, 0
	v_mov_b32_e32 v0, 0
	global_load_dword v0, v0, s[16:17] sc1
	s_waitcnt vmcnt(0)
	v_cmp_eq_u32_e32 vcc, v0, v1
	s_and_saveexec_b64 s[12:13], vcc
	s_cbranch_execz .LBB0_231
	s_add_u32 s14, s10, 0x32d0200
	s_addc_u32 s15, s11, 0
	s_mov_b32 s0, 1
	s_mov_b64 s[18:19], 0
	v_mov_b32_e32 v0, 0
	s_branch .LBB0_222

.LBB0_501:
	s_or_b64 exec, exec, s[12:13]
	v_cvt_f32_u32_e32 v4, v2
	s_waitcnt vmcnt(0)
	v_readfirstlane_b32 s1, v3
	v_sub_u32_e32 v3, 0, v2
	v_rcp_iflag_f32_e32 v4, v4
	v_add_u32_e32 v5, s1, v1
	v_mul_f32_e32 v4, 0x4f7ffffe, v4
	v_cvt_u32_f32_e32 v4, v4
	v_mul_lo_u32 v1, v3, v4
	v_mul_hi_u32 v1, v4, v1
	v_add_u32_e32 v1, v4, v1
	v_mul_hi_u32 v1, v5, v1
	v_mul_lo_u32 v3, v1, v2
	v_sub_u32_e32 v3, v5, v3
	v_add_u32_e32 v4, 1, v1
	v_cmp_ge_u32_e32 vcc, v3, v2
	s_nop 1
	v_cndmask_b32_e32 v1, v1, v4, vcc
	v_sub_u32_e32 v4, v3, v2
	v_cndmask_b32_e32 v3, v3, v4, vcc
	v_add_u32_e32 v4, 1, v1
	v_cmp_ge_u32_e32 vcc, v3, v2
	v_add_u32_e32 v3, 1, v5
	s_nop 0
	v_cndmask_b32_e32 v1, v1, v4, vcc
	v_mul_lo_u32 v4, v2, v1
	v_add_u32_e32 v2, v4, v2
	v_cmp_ne_u32_e32 vcc, v3, v2
	s_and_saveexec_b64 s[10:11], vcc
	s_xor_b64 s[10:11], exec, s[10:11]
	s_cbranch_execz .LBB0_515
	s_waitcnt lgkmcnt(0)
	v_cmp_eq_u32_e32 vcc, v5, v4
	s_cbranch_vccz .Lxbw_2
	buffer_wbl2 sc1
.Lxbw_2:
	s_add_u32 s18, s16, 0x32d3500
	s_addc_u32 s19, s17, 0
	v_mov_b32_e32 v0, 0
	global_load_dword v0, v0, s[18:19] sc1
	s_waitcnt vmcnt(0)
	v_cmp_eq_u32_e32 vcc, v0, v1
	s_and_saveexec_b64 s[12:13], vcc
	s_cbranch_execz .LBB0_514
	s_add_u32 s14, s16, 0x32d0200
	s_addc_u32 s15, s17, 0
	s_mov_b32 s1, 1
	s_mov_b64 s[24:25], 0
	v_mov_b32_e32 v0, 0
	s_branch .LBB0_505

.LBB0_561:
	s_or_b64 exec, exec, s[14:15]
	v_cvt_f32_u32_e32 v4, v2
	s_waitcnt vmcnt(0)
	v_readfirstlane_b32 s1, v3
	v_sub_u32_e32 v3, 0, v2
	v_rcp_iflag_f32_e32 v4, v4
	v_add_u32_e32 v5, s1, v1
	v_mul_f32_e32 v4, 0x4f7ffffe, v4
	v_cvt_u32_f32_e32 v4, v4
	v_mul_lo_u32 v1, v3, v4
	v_mul_hi_u32 v1, v4, v1
	v_add_u32_e32 v1, v4, v1
	v_mul_hi_u32 v1, v5, v1
	v_mul_lo_u32 v3, v1, v2
	v_sub_u32_e32 v3, v5, v3
	v_add_u32_e32 v4, 1, v1
	v_cmp_ge_u32_e32 vcc, v3, v2
	s_nop 1
	v_cndmask_b32_e32 v1, v1, v4, vcc
	v_sub_u32_e32 v4, v3, v2
	v_cndmask_b32_e32 v3, v3, v4, vcc
	v_add_u32_e32 v4, 1, v1
	v_cmp_ge_u32_e32 vcc, v3, v2
	v_add_u32_e32 v3, 1, v5
	s_nop 0
	v_cndmask_b32_e32 v1, v1, v4, vcc
	v_mul_lo_u32 v4, v2, v1
	v_add_u32_e32 v2, v4, v2
	v_cmp_ne_u32_e32 vcc, v3, v2
	s_and_saveexec_b64 s[12:13], vcc
	s_xor_b64 s[12:13], exec, s[12:13]
	s_cbranch_execz .LBB0_575
	s_waitcnt lgkmcnt(0)
	v_cmp_eq_u32_e32 vcc, v5, v4
	s_cbranch_vccz .Lxbw_3
	buffer_wbl2 sc1
.Lxbw_3:
	s_add_u32 s18, s6, 0x32d3500
	s_addc_u32 s19, s7, 0
	v_mov_b32_e32 v0, 0
	global_load_dword v0, v0, s[18:19] sc1
	s_waitcnt vmcnt(0)
	v_cmp_eq_u32_e32 vcc, v0, v1
	s_and_saveexec_b64 s[14:15], vcc
	s_cbranch_execz .LBB0_574
	s_add_u32 s16, s6, 0x32d0200
	s_addc_u32 s17, s7, 0
	s_mov_b32 s1, 1
	s_mov_b64 s[24:25], 0
	v_mov_b32_e32 v0, 0
	s_branch .LBB0_565

.LBB0_848:
	s_or_b64 exec, exec, s[10:11]
	v_cvt_f32_u32_e32 v4, v2
	s_waitcnt vmcnt(0)
	v_readfirstlane_b32 s0, v3
	v_sub_u32_e32 v3, 0, v2
	v_rcp_iflag_f32_e32 v4, v4
	v_add_u32_e32 v5, s0, v1
	v_mul_f32_e32 v4, 0x4f7ffffe, v4
	v_cvt_u32_f32_e32 v4, v4
	v_mul_lo_u32 v1, v3, v4
	v_mul_hi_u32 v1, v4, v1
	v_add_u32_e32 v1, v4, v1
	v_mul_hi_u32 v1, v5, v1
	v_mul_lo_u32 v3, v1, v2
	v_sub_u32_e32 v3, v5, v3
	v_add_u32_e32 v4, 1, v1
	v_cmp_ge_u32_e32 vcc, v3, v2
	s_nop 1
	v_cndmask_b32_e32 v1, v1, v4, vcc
	v_sub_u32_e32 v4, v3, v2
	v_cndmask_b32_e32 v3, v3, v4, vcc
	v_add_u32_e32 v4, 1, v1
	v_cmp_ge_u32_e32 vcc, v3, v2
	v_add_u32_e32 v3, 1, v5
	s_nop 0
	v_cndmask_b32_e32 v1, v1, v4, vcc
	v_mul_lo_u32 v4, v2, v1
	v_add_u32_e32 v2, v4, v2
	v_cmp_ne_u32_e32 vcc, v3, v2
	s_and_saveexec_b64 s[0:1], vcc
	s_xor_b64 s[8:9], exec, s[0:1]
	s_cbranch_execz .LBB0_862
	s_waitcnt lgkmcnt(0)
	v_cmp_eq_u32_e32 vcc, v5, v4
	s_cbranch_vccz .Lxbw_4
	buffer_wbl2 sc1
.Lxbw_4:
	s_add_u32 s14, s18, 0x32d3500
	s_addc_u32 s15, s19, 0
	v_mov_b32_e32 v0, 0
	global_load_dword v0, v0, s[14:15] sc1
	s_waitcnt vmcnt(0)
	v_cmp_eq_u32_e32 vcc, v0, v1
	s_and_saveexec_b64 s[10:11], vcc
	s_cbranch_execz .LBB0_861
	s_add_u32 s12, s18, 0x32d0200
	s_addc_u32 s13, s19, 0
	s_mov_b32 s0, 1
	s_mov_b64 s[16:17], 0
	v_mov_b32_e32 v0, 0
	s_branch .LBB0_852

.Lxbw_5:
	s_add_u32 s18, s14, 0x32d3500
	s_addc_u32 s19, s15, 0
	v_mov_b32_e32 v0, 0
	global_load_dword v0, v0, s[18:19] sc1
	s_waitcnt vmcnt(0)
	v_cmp_eq_u32_e32 vcc, v0, v1
	s_and_saveexec_b64 s[12:13], vcc
	s_cbranch_execz .LBB0_951
	s_add_u32 s16, s14, 0x32d0200
	s_addc_u32 s17, s15, 0
	s_mov_b32 s0, 1
	s_mov_b64 s[24:25], 0
	v_mov_b32_e32 v0, 0
	s_branch .LBB0_942

.LBB0_1010:
	s_or_b64 exec, exec, s[16:17]
	v_cvt_f32_u32_e32 v4, v2
	s_waitcnt vmcnt(0)
	v_readfirstlane_b32 s0, v3
	v_sub_u32_e32 v3, 0, v2
	v_rcp_iflag_f32_e32 v4, v4
	v_add_u32_e32 v5, s0, v1
	v_mul_f32_e32 v4, 0x4f7ffffe, v4
	v_cvt_u32_f32_e32 v4, v4
	v_mul_lo_u32 v1, v3, v4
	v_mul_hi_u32 v1, v4, v1
	v_add_u32_e32 v1, v4, v1
	v_mul_hi_u32 v1, v5, v1
	v_mul_lo_u32 v3, v1, v2
	v_sub_u32_e32 v3, v5, v3
	v_add_u32_e32 v4, 1, v1
	v_cmp_ge_u32_e32 vcc, v3, v2
	s_nop 1
	v_cndmask_b32_e32 v1, v1, v4, vcc
	v_sub_u32_e32 v4, v3, v2
	v_cndmask_b32_e32 v3, v3, v4, vcc
	v_add_u32_e32 v4, 1, v1
	v_cmp_ge_u32_e32 vcc, v3, v2
	v_add_u32_e32 v3, 1, v5
	s_nop 0
	v_cndmask_b32_e32 v1, v1, v4, vcc
	v_mul_lo_u32 v4, v2, v1
	v_add_u32_e32 v2, v4, v2
	v_cmp_ne_u32_e32 vcc, v3, v2
	s_and_saveexec_b64 s[0:1], vcc
	s_xor_b64 s[12:13], exec, s[0:1]
	s_cbranch_execz .LBB0_1024
	s_waitcnt lgkmcnt(0)
	v_cmp_eq_u32_e32 vcc, v5, v4
	s_cbranch_vccz .Lxbw_6
	buffer_wbl2 sc1
.Lxbw_6:
	s_add_u32 s24, s14, 0x32d3500
	s_addc_u32 s25, s15, 0
	v_mov_b32_e32 v0, 0
	global_load_dword v0, v0, s[24:25] sc1
	s_waitcnt vmcnt(0)
	v_cmp_eq_u32_e32 vcc, v0, v1
	s_and_saveexec_b64 s[16:17], vcc
	s_cbranch_execz .LBB0_1023
	s_add_u32 s18, s14, 0x32d0200
	s_addc_u32 s19, s15, 0
	s_mov_b32 s0, 1
	s_mov_b64 s[26:27], 0
	v_mov_b32_e32 v0, 0
	s_branch .LBB0_1014

.LBB0_1100:
	s_or_b64 exec, exec, s[16:17]
	v_cvt_f32_u32_e32 v4, v2
	s_waitcnt vmcnt(0)
	v_readfirstlane_b32 s0, v3
	v_sub_u32_e32 v3, 0, v2
	v_rcp_iflag_f32_e32 v4, v4
	v_add_u32_e32 v5, s0, v1
	v_mul_f32_e32 v4, 0x4f7ffffe, v4
	v_cvt_u32_f32_e32 v4, v4
	v_mul_lo_u32 v1, v3, v4
	v_mul_hi_u32 v1, v4, v1
	v_add_u32_e32 v1, v4, v1
	v_mul_hi_u32 v1, v5, v1
	v_mul_lo_u32 v3, v1, v2
	v_sub_u32_e32 v3, v5, v3
	v_add_u32_e32 v4, 1, v1
	v_cmp_ge_u32_e32 vcc, v3, v2
	s_nop 1
	v_cndmask_b32_e32 v1, v1, v4, vcc
	v_sub_u32_e32 v4, v3, v2
	v_cndmask_b32_e32 v3, v3, v4, vcc
	v_add_u32_e32 v4, 1, v1
	v_cmp_ge_u32_e32 vcc, v3, v2
	v_add_u32_e32 v3, 1, v5
	s_nop 0
	v_cndmask_b32_e32 v1, v1, v4, vcc
	v_mul_lo_u32 v4, v2, v1
	v_add_u32_e32 v2, v4, v2
	v_cmp_ne_u32_e32 vcc, v3, v2
	s_and_saveexec_b64 s[0:1], vcc
	s_xor_b64 s[14:15], exec, s[0:1]
	s_cbranch_execz .LBB0_1114
	s_waitcnt lgkmcnt(0)
	v_cmp_eq_u32_e32 vcc, v5, v4
	s_cbranch_vccz .Lxbw_7
	buffer_wbl2 sc1
.Lxbw_7:
	s_add_u32 s24, s12, 0x32d3500
	s_addc_u32 s25, s13, 0
	v_mov_b32_e32 v0, 0
	global_load_dword v0, v0, s[24:25] sc1
	s_waitcnt vmcnt(0)
	v_cmp_eq_u32_e32 vcc, v0, v1
	s_and_saveexec_b64 s[16:17], vcc
	s_cbranch_execz .LBB0_1113
	s_add_u32 s18, s12, 0x32d0200
	s_addc_u32 s19, s13, 0
	s_mov_b32 s0, 1
	s_mov_b64 s[26:27], 0
	v_mov_b32_e32 v0, 0
	s_branch .LBB0_1104

.Lxbw_9:
	s_add_u32 s26, s18, 0x32d3500
	s_addc_u32 s27, s19, 0
	v_mov_b32_e32 v0, 0
	global_load_dword v0, v0, s[26:27] sc1
	s_waitcnt vmcnt(0)
	v_cmp_eq_u32_e32 vcc, v0, v1
	s_and_saveexec_b64 s[16:17], vcc
	s_cbranch_execz .LBB0_1405
	s_add_u32 s24, s18, 0x32d0200
	s_addc_u32 s25, s19, 0
	s_mov_b32 s0, 1
	s_mov_b64 s[28:29], 0
	v_mov_b32_e32 v0, 0
	s_branch .LBB0_1396

.LBB0_1699:
	s_or_b64 exec, exec, s[16:17]
	v_cvt_f32_u32_e32 v4, v2
	s_waitcnt vmcnt(0)
	v_readfirstlane_b32 s1, v3
	v_sub_u32_e32 v3, 0, v2
	v_rcp_iflag_f32_e32 v4, v4
	v_add_u32_e32 v5, s1, v1
	v_mul_f32_e32 v4, 0x4f7ffffe, v4
	v_cvt_u32_f32_e32 v4, v4
	v_mul_lo_u32 v1, v3, v4
	v_mul_hi_u32 v1, v4, v1
	v_add_u32_e32 v1, v4, v1
	v_mul_hi_u32 v1, v5, v1
	v_mul_lo_u32 v3, v1, v2
	v_sub_u32_e32 v3, v5, v3
	v_add_u32_e32 v4, 1, v1
	v_cmp_ge_u32_e32 vcc, v3, v2
	s_nop 1
	v_cndmask_b32_e32 v1, v1, v4, vcc
	v_sub_u32_e32 v4, v3, v2
	v_cndmask_b32_e32 v3, v3, v4, vcc
	v_add_u32_e32 v4, 1, v1
	v_cmp_ge_u32_e32 vcc, v3, v2
	v_add_u32_e32 v3, 1, v5
	s_nop 0
	v_cndmask_b32_e32 v1, v1, v4, vcc
	v_mul_lo_u32 v4, v2, v1
	v_add_u32_e32 v2, v4, v2
	v_cmp_ne_u32_e32 vcc, v3, v2
	s_and_saveexec_b64 s[14:15], vcc
	s_xor_b64 s[14:15], exec, s[14:15]
	s_cbranch_execz .LBB0_1713
	s_waitcnt lgkmcnt(0)
	v_cmp_eq_u32_e32 vcc, v5, v4
	s_cbranch_vccz .Lxbw_11
	buffer_wbl2 sc1
.Lxbw_11:
	s_add_u32 s24, s30, 0x32d3500
	s_addc_u32 s25, s31, 0
	v_mov_b32_e32 v0, 0
	global_load_dword v0, v0, s[24:25] sc1
	s_waitcnt vmcnt(0)
	v_cmp_eq_u32_e32 vcc, v0, v1
	s_and_saveexec_b64 s[16:17], vcc
	s_cbranch_execz .LBB0_1712
	s_add_u32 s18, s30, 0x32d0200
	s_addc_u32 s19, s31, 0
	s_mov_b32 s1, 1
	s_mov_b64 s[26:27], 0
	v_mov_b32_e32 v0, 0
	s_branch .LBB0_1703

.LBB0_1842:
	s_or_b64 exec, exec, s[14:15]
	v_cvt_f32_u32_e32 v4, v2
	s_waitcnt vmcnt(0)
	v_readfirstlane_b32 s0, v3
	v_sub_u32_e32 v3, 0, v2
	v_rcp_iflag_f32_e32 v4, v4
	v_add_u32_e32 v5, s0, v1
	v_mul_f32_e32 v4, 0x4f7ffffe, v4
	v_cvt_u32_f32_e32 v4, v4
	v_mul_lo_u32 v1, v3, v4
	v_mul_hi_u32 v1, v4, v1
	v_add_u32_e32 v1, v4, v1
	v_mul_hi_u32 v1, v5, v1
	v_mul_lo_u32 v3, v1, v2
	v_sub_u32_e32 v3, v5, v3
	v_add_u32_e32 v4, 1, v1
	v_cmp_ge_u32_e32 vcc, v3, v2
	s_nop 1
	v_cndmask_b32_e32 v1, v1, v4, vcc
	v_sub_u32_e32 v4, v3, v2
	v_cndmask_b32_e32 v3, v3, v4, vcc
	v_add_u32_e32 v4, 1, v1
	v_cmp_ge_u32_e32 vcc, v3, v2
	v_add_u32_e32 v3, 1, v5
	s_nop 0
	v_cndmask_b32_e32 v1, v1, v4, vcc
	v_mul_lo_u32 v4, v2, v1
	v_add_u32_e32 v2, v4, v2
	v_cmp_ne_u32_e32 vcc, v3, v2
	s_and_saveexec_b64 s[0:1], vcc
	s_xor_b64 s[12:13], exec, s[0:1]
	s_cbranch_execz .LBB0_1856
	s_waitcnt lgkmcnt(0)
	v_cmp_eq_u32_e32 vcc, v5, v4
	s_cbranch_vccz .Lxbw_12
	buffer_wbl2 sc1
.Lxbw_12:
	s_add_u32 s18, s30, 0x32d3500
	s_addc_u32 s19, s31, 0
	v_mov_b32_e32 v0, 0
	global_load_dword v0, v0, s[18:19] sc1
	s_waitcnt vmcnt(0)
	v_cmp_eq_u32_e32 vcc, v0, v1
	s_and_saveexec_b64 s[14:15], vcc
	s_cbranch_execz .LBB0_1855
	s_add_u32 s16, s30, 0x32d0200
	s_addc_u32 s17, s31, 0
	s_mov_b32 s0, 1
	s_mov_b64 s[24:25], 0
	v_mov_b32_e32 v0, 0
	s_branch .LBB0_1846

.LBB0_2004:
	s_or_b64 exec, exec, s[14:15]
	v_cvt_f32_u32_e32 v4, v2
	s_waitcnt vmcnt(0)
	v_readfirstlane_b32 s0, v3
	v_sub_u32_e32 v3, 0, v2
	v_rcp_iflag_f32_e32 v4, v4
	v_add_u32_e32 v5, s0, v1
	v_mul_f32_e32 v4, 0x4f7ffffe, v4
	v_cvt_u32_f32_e32 v4, v4
	v_mul_lo_u32 v1, v3, v4
	v_mul_hi_u32 v1, v4, v1
	v_add_u32_e32 v1, v4, v1
	v_mul_hi_u32 v1, v5, v1
	v_mul_lo_u32 v3, v1, v2
	v_sub_u32_e32 v3, v5, v3
	v_add_u32_e32 v4, 1, v1
	v_cmp_ge_u32_e32 vcc, v3, v2
	s_nop 1
	v_cndmask_b32_e32 v1, v1, v4, vcc
	v_sub_u32_e32 v4, v3, v2
	v_cndmask_b32_e32 v3, v3, v4, vcc
	v_add_u32_e32 v4, 1, v1
	v_cmp_ge_u32_e32 vcc, v3, v2
	v_add_u32_e32 v3, 1, v5
	s_nop 0
	v_cndmask_b32_e32 v1, v1, v4, vcc
	v_mul_lo_u32 v4, v2, v1
	v_add_u32_e32 v2, v4, v2
	v_cmp_ne_u32_e32 vcc, v3, v2
	s_and_saveexec_b64 s[0:1], vcc
	s_xor_b64 s[10:11], exec, s[0:1]
	s_cbranch_execz .LBB0_2018
	s_waitcnt lgkmcnt(0)
	v_cmp_eq_u32_e32 vcc, v5, v4
	s_cbranch_vccz .Lxbw_14
	buffer_wbl2 sc1
.Lxbw_14:
	s_add_u32 s18, s12, 0x32d3500
	s_addc_u32 s19, s13, 0
	v_mov_b32_e32 v0, 0
	global_load_dword v0, v0, s[18:19] sc1
	s_waitcnt vmcnt(0)
	v_cmp_eq_u32_e32 vcc, v0, v1
	s_and_saveexec_b64 s[14:15], vcc
	s_cbranch_execz .LBB0_2017
	s_add_u32 s16, s12, 0x32d0200
	s_addc_u32 s17, s13, 0
	s_mov_b32 s0, 1
	s_mov_b64 s[24:25], 0
	v_mov_b32_e32 v0, 0
	s_branch .LBB0_2008

.LBB0_2094:
	s_or_b64 exec, exec, s[10:11]
	v_cvt_f32_u32_e32 v4, v2
	s_waitcnt vmcnt(0)
	v_readfirstlane_b32 s0, v3
	v_sub_u32_e32 v3, 0, v2
	v_rcp_iflag_f32_e32 v4, v4
	v_add_u32_e32 v5, s0, v1
	v_mul_f32_e32 v4, 0x4f7ffffe, v4
	v_cvt_u32_f32_e32 v4, v4
	v_mul_lo_u32 v1, v3, v4
	v_mul_hi_u32 v1, v4, v1
	v_add_u32_e32 v1, v4, v1
	v_mul_hi_u32 v1, v5, v1
	v_mul_lo_u32 v3, v1, v2
	v_sub_u32_e32 v3, v5, v3
	v_add_u32_e32 v4, 1, v1
	v_cmp_ge_u32_e32 vcc, v3, v2
	s_nop 1
	v_cndmask_b32_e32 v1, v1, v4, vcc
	v_sub_u32_e32 v4, v3, v2
	v_cndmask_b32_e32 v3, v3, v4, vcc
	v_add_u32_e32 v4, 1, v1
	v_cmp_ge_u32_e32 vcc, v3, v2
	v_add_u32_e32 v3, 1, v5
	s_nop 0
	v_cndmask_b32_e32 v1, v1, v4, vcc
	v_mul_lo_u32 v4, v2, v1
	v_add_u32_e32 v2, v4, v2
	v_cmp_ne_u32_e32 vcc, v3, v2
	s_and_saveexec_b64 s[0:1], vcc
	s_xor_b64 s[6:7], exec, s[0:1]
	s_cbranch_execz .LBB0_2108
	s_waitcnt lgkmcnt(0)
	v_cmp_eq_u32_e32 vcc, v5, v4
	s_cbranch_vccz .Lxbw_15
	buffer_wbl2 sc1
.Lxbw_15:
	s_add_u32 s14, s8, 0x32d3500
	s_addc_u32 s15, s9, 0
	v_mov_b32_e32 v0, 0
	global_load_dword v0, v0, s[14:15] sc1
	s_waitcnt vmcnt(0)
	v_cmp_eq_u32_e32 vcc, v0, v1
	s_and_saveexec_b64 s[10:11], vcc
	s_cbranch_execz .LBB0_2107
	s_add_u32 s12, s8, 0x32d0200
	s_addc_u32 s13, s9, 0
	s_mov_b32 s0, 1
	s_mov_b64 s[16:17], 0
	v_mov_b32_e32 v0, 0
	s_branch .LBB0_2098
